# v96 stack + P8 epilogue: per-row sigmoid constants (k*rs, rs*rs) stored next to the rs table in LDS once per row panel instead of two multiplies per row block in every unit
# speedup vs baseline: 1.0048x; 1.0044x over previous
; #define PG8_LAS __attribute__((address_space(3)))
; __device__ __forceinline__ const PG8_LAS float* rs_table(const float* SS, int r0, PG8_LAS unsigned char* xl) {
;     PG8_LAS float* S = (PG8_LAS float*)(xl + 8192 + 256); const int tid = threadIdx.x;
;     if (tid < 256) { const f32x4 p = *(const f32x4*)(SS + (size_t)(r0 + tid) * 4); S[tid] = 1.0f / sqrtf(((p[0] + p[1]) + (p[2] + p[3])) * (1.f / DM) + EPS); }
;     asm volatile("s_waitcnt vmcnt(0) lgkmcnt(0)" ::: "memory"); __builtin_amdgcn_s_barrier(); asm volatile("" ::: "memory");
;     __device__ __forceinline__ void operator()(Acc& acc, const Unit& u, int wr, int wc, int fr, int fq, PG8_LAS unsigned char* xl) const {
;     ...
;             for (int m = 0; m < 4; ++m) { const int rl = ai * HALF + wr * 64 + m * 16 + fr; const int row = u.r0 + rl; const float s = S[rl], cs = -LOG2E * s, s2 = s * s;
.LBB0_828:
	s_cmp_eq_u32 s60, s99
	s_cbranch_scc1 .Lrs8_skip
	s_mov_b32 s99, s60
	s_and_saveexec_b64 s[30:31], s[4:5]
	s_cbranch_execz .LBB0_830
	v_add_u32_e32 v170, s60, v220
	v_ashrrev_i32_e32 v171, 31, v170
	v_lshl_add_u64 v[170:171], v[170:171], 4, s[14:15]
	flat_load_dwordx4 v[170:173], v[170:171]
	s_waitcnt vmcnt(0) lgkmcnt(0)
	v_mov_b32_e32 v174, v171
	v_mov_b32_e32 v175, v172
	v_mov_b32_e32 v171, v173
	v_pk_add_f32 v[170:171], v[174:175], v[170:171]
	s_nop 0
	v_add_f32_e32 v169, v170, v171
	v_fmamk_f32 v169, v169, 0x3a800000, v167
	v_mul_f32_e32 v170, 0x4f800000, v169
	v_cmp_gt_f32_e32 vcc, s63, v169
	s_nop 1
	v_cndmask_b32_e32 v169, v169, v170, vcc
	v_sqrt_f32_e32 v170, v169
	s_nop 0
	v_add_u32_e32 v171, -1, v170
	v_add_u32_e32 v172, 1, v170
	v_fma_f32 v173, -v171, v170, v169
	v_fma_f32 v174, -v172, v170, v169
	v_cmp_ge_f32_e64 s[2:3], 0, v173
	s_nop 1
	v_cndmask_b32_e64 v170, v170, v171, s[2:3]
	v_cmp_lt_f32_e64 s[2:3], 0, v174
	s_nop 1
	v_cndmask_b32_e64 v170, v170, v172, s[2:3]
	v_mul_f32_e32 v171, 0x37800000, v170
	v_cndmask_b32_e32 v170, v170, v171, vcc
	v_cmp_class_f32_e32 vcc, v169, v168
	s_nop 1
	v_cndmask_b32_e32 v169, v170, v169, vcc
	v_div_scale_f32 v170, s[2:3], v169, v169, 1.0
	v_rcp_f32_e32 v171, v170
	v_div_scale_f32 v172, vcc, 1.0, v169, 1.0
	v_fma_f32 v173, -v170, v171, 1.0
	v_fmac_f32_e32 v171, v173, v171
	v_mul_f32_e32 v173, v172, v171
	v_fma_f32 v174, -v170, v173, v172
	v_fmac_f32_e32 v173, v174, v171
	v_fma_f32 v170, -v170, v173, v172
	v_div_fmas_f32 v170, v170, v171, v173
	v_div_fixup_f32 v169, v170, v169, 1.0
	ds_write_b32 v154, v169
	v_mul_f32_e32 v170, 0xbfb8aa3b, v169
	v_mul_f32_e32 v171, v169, v169
	ds_write_b32 v154, v170 offset:1280
	ds_write_b32 v154, v171 offset:2560

; __device__ __forceinline__ u32x4 pack8(f32x4 v0, f32x4 v1) { u32x4 w; w.x = cvt_pk_bf16(v0[0], v0[1]); w.y = cvt_pk_bf16(v0[2], v0[3]); w.z = cvt_pk_bf16(v1[0], v1[1]); w.w = cvt_pk_bf16(v1[2], v1[3]); return w; }
;     __device__ __forceinline__ void operator()(Acc& acc, const Unit& u, int wr, int wc, int fr, int fq, PG8_LAS unsigned char* xl) const {
;     ...
;             for (int m = 0; m < 4; ++m) { const int rl = ai * HALF + wr * 64 + m * 16 + fr; const int row = u.r0 + rl; const float s = S[rl], cs = -LOG2E * s, s2 = s * s;
;                 f32x4 o[2];
; #pragma unroll
;                 for (int n = 0; n < 2; ++n) { const f32x4 g = acc[ai][0][m][n], gu = acc[ai][0][m][n] * acc[ai][1][m][n]; f32x4 r;
; #pragma unroll
;                     for (int e = 0; e < 4; ++e) r[e] = gu[e] * (s2 * __builtin_amdgcn_rcpf(1.f + __builtin_amdgcn_exp2f(cs * g[e])));
;                     o[n] = r; }
;                 *(u32x4*)(H + (size_t)row * ldc + (u.c0 >> 1) + wc * 32 + 8 * fq) = pack8(o[0], o[1]); }
.Lrs8_skip:
	ds_read_b32 v184, v148 offset:1280
	ds_read_b32 v200, v148 offset:2560
	ds_read_b32 v186, v150 offset:1280
	ds_read_b32 v202, v150 offset:2560
	ds_read_b32 v188, v152 offset:1280
	ds_read_b32 v204, v152 offset:2560
	ds_read_b32 v190, v155 offset:1280
	ds_read_b32 v206, v155 offset:2560
	ds_read_b32 v192, v157 offset:1280
	ds_read_b32 v208, v157 offset:2560
	ds_read_b32 v194, v159 offset:1280
	ds_read_b32 v210, v159 offset:2560
	ds_read_b32 v196, v161 offset:1280
	ds_read_b32 v212, v161 offset:2560
	ds_read_b32 v198, v163 offset:1280
	ds_read_b32 v214, v163 offset:2560
	s_ashr_i32 s2, s33, 1
	s_ashr_i32 s3, s2, 31
	s_lshl_b64 s[2:3], s[2:3], 1
	v_mov_b64_e32 v[170:171], s[12:13]
	v_mov_b32_e32 v180, 1.0
	v_pk_mul_f32 v[120:121], v[124:125], v[120:121]
	v_pk_mul_f32 v[122:123], v[126:127], v[122:123]
	v_pk_mul_f32 v[112:113], v[116:117], v[112:113]
	v_pk_mul_f32 v[114:115], v[118:119], v[114:115]
	s_waitcnt lgkmcnt(0)
	v_pk_mul_f32 v[124:125], v[124:125], v[184:185] op_sel_hi:[1,0]
	v_pk_mul_f32 v[126:127], v[126:127], v[184:185] op_sel_hi:[1,0]
	v_pk_mul_f32 v[116:117], v[116:117], v[184:185] op_sel_hi:[1,0]
	v_pk_mul_f32 v[118:119], v[118:119], v[184:185] op_sel_hi:[1,0]
	v_exp_f32_e32 v124, v124
	v_exp_f32_e32 v125, v125
	v_exp_f32_e32 v126, v126
	v_exp_f32_e32 v127, v127
	v_exp_f32_e32 v116, v116
	v_exp_f32_e32 v117, v117
	v_exp_f32_e32 v118, v118
	v_exp_f32_e32 v119, v119
	v_pk_add_f32 v[124:125], v[124:125], v[180:181] op_sel_hi:[1,0]
	v_pk_add_f32 v[126:127], v[126:127], v[180:181] op_sel_hi:[1,0]
	v_pk_add_f32 v[116:117], v[116:117], v[180:181] op_sel_hi:[1,0]
	v_pk_add_f32 v[118:119], v[118:119], v[180:181] op_sel_hi:[1,0]
	v_add_u32_e32 v172, s60, v146
	v_rcp_f32_e32 v124, v124
	v_rcp_f32_e32 v125, v125
	v_rcp_f32_e32 v126, v126
	v_rcp_f32_e32 v127, v127
	v_mad_i64_i32 v[172:173], s[30:31], v172, s64, v[170:171]
	v_rcp_f32_e32 v116, v116
	v_rcp_f32_e32 v117, v117
	v_rcp_f32_e32 v118, v118
	v_rcp_f32_e32 v119, v119
	v_lshl_add_u64 v[172:173], v[172:173], 0, s[2:3]
	v_lshl_add_u64 v[172:173], v[172:173], 0, s[8:9]
	v_lshl_add_u64 v[172:173], v[172:173], 0, v[136:137]
	v_pk_mul_f32 v[124:125], v[124:125], v[200:201] op_sel_hi:[1,0]
	v_pk_mul_f32 v[126:127], v[126:127], v[200:201] op_sel_hi:[1,0]
	v_pk_mul_f32 v[116:117], v[116:117], v[200:201] op_sel_hi:[1,0]
	v_pk_mul_f32 v[118:119], v[118:119], v[200:201] op_sel_hi:[1,0]
	v_pk_mul_f32 v[120:121], v[120:121], v[124:125]
	v_pk_mul_f32 v[122:123], v[122:123], v[126:127]
	v_pk_mul_f32 v[112:113], v[112:113], v[116:117]
	v_pk_mul_f32 v[114:115], v[114:115], v[118:119]
	v_cvt_pk_bf16_f32 v124, v120, v121
	v_cvt_pk_bf16_f32 v125, v122, v123
	v_cvt_pk_bf16_f32 v126, v112, v113
	v_cvt_pk_bf16_f32 v127, v114, v115
	flat_store_dwordx4 v[172:173], v[124:127]
	v_pk_mul_f32 v[104:105], v[108:109], v[104:105]
	v_pk_mul_f32 v[106:107], v[110:111], v[106:107]
	v_pk_mul_f32 v[96:97], v[100:101], v[96:97]
	v_pk_mul_f32 v[98:99], v[102:103], v[98:99]
	v_pk_mul_f32 v[108:109], v[108:109], v[186:187] op_sel_hi:[1,0]
	v_pk_mul_f32 v[110:111], v[110:111], v[186:187] op_sel_hi:[1,0]
	v_pk_mul_f32 v[100:101], v[100:101], v[186:187] op_sel_hi:[1,0]
	v_pk_mul_f32 v[102:103], v[102:103], v[186:187] op_sel_hi:[1,0]
	v_exp_f32_e32 v108, v108
	v_exp_f32_e32 v109, v109
	v_exp_f32_e32 v110, v110
	v_exp_f32_e32 v111, v111
	v_exp_f32_e32 v100, v100
	v_exp_f32_e32 v101, v101
	v_exp_f32_e32 v102, v102
	v_exp_f32_e32 v103, v103
	v_pk_add_f32 v[108:109], v[108:109], v[180:181] op_sel_hi:[1,0]
	v_pk_add_f32 v[110:111], v[110:111], v[180:181] op_sel_hi:[1,0]
	v_pk_add_f32 v[100:101], v[100:101], v[180:181] op_sel_hi:[1,0]
	v_pk_add_f32 v[102:103], v[102:103], v[180:181] op_sel_hi:[1,0]
	v_add_co_u32_e32 v172, vcc, 0x16000, v172
	v_rcp_f32_e32 v108, v108
	v_rcp_f32_e32 v109, v109
	v_rcp_f32_e32 v110, v110
	v_rcp_f32_e32 v111, v111
	v_addc_co_u32_e32 v173, vcc, 0, v173, vcc
	v_rcp_f32_e32 v100, v100
	v_rcp_f32_e32 v101, v101
	v_rcp_f32_e32 v102, v102
	v_rcp_f32_e32 v103, v103
	v_pk_mul_f32 v[108:109], v[108:109], v[202:203] op_sel_hi:[1,0]
	v_pk_mul_f32 v[110:111], v[110:111], v[202:203] op_sel_hi:[1,0]
	v_pk_mul_f32 v[100:101], v[100:101], v[202:203] op_sel_hi:[1,0]
	v_pk_mul_f32 v[102:103], v[102:103], v[202:203] op_sel_hi:[1,0]
	v_pk_mul_f32 v[104:105], v[104:105], v[108:109]
	v_pk_mul_f32 v[106:107], v[106:107], v[110:111]
	v_pk_mul_f32 v[96:97], v[96:97], v[100:101]
	v_pk_mul_f32 v[98:99], v[98:99], v[102:103]
	v_cvt_pk_bf16_f32 v108, v104, v105
	v_cvt_pk_bf16_f32 v109, v106, v107
	v_cvt_pk_bf16_f32 v110, v96, v97
	v_cvt_pk_bf16_f32 v111, v98, v99
	flat_store_dwordx4 v[172:173], v[108:111]
	v_pk_mul_f32 v[88:89], v[92:93], v[88:89]
	v_pk_mul_f32 v[90:91], v[94:95], v[90:91]
	v_pk_mul_f32 v[80:81], v[84:85], v[80:81]
	v_pk_mul_f32 v[82:83], v[86:87], v[82:83]
	v_pk_mul_f32 v[92:93], v[92:93], v[188:189] op_sel_hi:[1,0]
	v_pk_mul_f32 v[94:95], v[94:95], v[188:189] op_sel_hi:[1,0]
	v_pk_mul_f32 v[84:85], v[84:85], v[188:189] op_sel_hi:[1,0]
	v_pk_mul_f32 v[86:87], v[86:87], v[188:189] op_sel_hi:[1,0]
	v_exp_f32_e32 v92, v92
	v_exp_f32_e32 v93, v93
	v_exp_f32_e32 v94, v94
	v_exp_f32_e32 v95, v95
	v_exp_f32_e32 v84, v84
	v_exp_f32_e32 v85, v85
	v_exp_f32_e32 v86, v86
	v_exp_f32_e32 v87, v87
	v_pk_add_f32 v[92:93], v[92:93], v[180:181] op_sel_hi:[1,0]
	v_pk_add_f32 v[94:95], v[94:95], v[180:181] op_sel_hi:[1,0]
	v_pk_add_f32 v[84:85], v[84:85], v[180:181] op_sel_hi:[1,0]
	v_pk_add_f32 v[86:87], v[86:87], v[180:181] op_sel_hi:[1,0]
	v_add_co_u32_e32 v172, vcc, 0x16000, v172
	v_rcp_f32_e32 v92, v92
	v_rcp_f32_e32 v93, v93
	v_rcp_f32_e32 v94, v94
	v_rcp_f32_e32 v95, v95
	v_addc_co_u32_e32 v173, vcc, 0, v173, vcc
; __device__ __forceinline__ u32x4 pack8(f32x4 v0, f32x4 v1) { u32x4 w; w.x = cvt_pk_bf16(v0[0], v0[1]); w.y = cvt_pk_bf16(v0[2], v0[3]); w.z = cvt_pk_bf16(v1[0], v1[1]); w.w = cvt_pk_bf16(v1[2], v1[3]); return w; }
;     __device__ __forceinline__ void operator()(Acc& acc, const Unit& u, int wr, int wc, int fr, int fq, PG8_LAS unsigned char* xl) const {
;     ...
;             for (int m = 0; m < 4; ++m) { const int rl = ai * HALF + wr * 64 + m * 16 + fr; const int row = u.r0 + rl; const float s = S[rl], cs = -LOG2E * s, s2 = s * s;
;                 f32x4 o[2];
; #pragma unroll
;                 for (int n = 0; n < 2; ++n) { const f32x4 g = acc[ai][0][m][n], gu = acc[ai][0][m][n] * acc[ai][1][m][n]; f32x4 r;
; #pragma unroll
;                     for (int e = 0; e < 4; ++e) r[e] = gu[e] * (s2 * __builtin_amdgcn_rcpf(1.f + __builtin_amdgcn_exp2f(cs * g[e])));
;                     o[n] = r; }
;                 *(u32x4*)(H + (size_t)row * ldc + (u.c0 >> 1) + wc * 32 + 8 * fq) = pack8(o[0], o[1]); }
	v_rcp_f32_e32 v84, v84
	v_rcp_f32_e32 v85, v85
	v_rcp_f32_e32 v86, v86
	v_rcp_f32_e32 v87, v87
	v_pk_mul_f32 v[92:93], v[92:93], v[204:205] op_sel_hi:[1,0]
	v_pk_mul_f32 v[94:95], v[94:95], v[204:205] op_sel_hi:[1,0]
	v_pk_mul_f32 v[84:85], v[84:85], v[204:205] op_sel_hi:[1,0]
	v_pk_mul_f32 v[86:87], v[86:87], v[204:205] op_sel_hi:[1,0]
	v_pk_mul_f32 v[88:89], v[88:89], v[92:93]
	v_pk_mul_f32 v[90:91], v[90:91], v[94:95]
	v_pk_mul_f32 v[80:81], v[80:81], v[84:85]
	v_pk_mul_f32 v[82:83], v[82:83], v[86:87]
	v_cvt_pk_bf16_f32 v92, v88, v89
	v_cvt_pk_bf16_f32 v93, v90, v91
	v_cvt_pk_bf16_f32 v94, v80, v81
	v_cvt_pk_bf16_f32 v95, v82, v83
	flat_store_dwordx4 v[172:173], v[92:95]
	v_pk_mul_f32 v[72:73], v[76:77], v[72:73]
	v_pk_mul_f32 v[74:75], v[78:79], v[74:75]
	v_pk_mul_f32 v[64:65], v[68:69], v[64:65]
	v_pk_mul_f32 v[66:67], v[70:71], v[66:67]
	v_pk_mul_f32 v[76:77], v[76:77], v[190:191] op_sel_hi:[1,0]
	v_pk_mul_f32 v[78:79], v[78:79], v[190:191] op_sel_hi:[1,0]
	v_pk_mul_f32 v[68:69], v[68:69], v[190:191] op_sel_hi:[1,0]
	v_pk_mul_f32 v[70:71], v[70:71], v[190:191] op_sel_hi:[1,0]
	v_exp_f32_e32 v76, v76
	v_exp_f32_e32 v77, v77
	v_exp_f32_e32 v78, v78
	v_exp_f32_e32 v79, v79
	v_exp_f32_e32 v68, v68
	v_exp_f32_e32 v69, v69
	v_exp_f32_e32 v70, v70
	v_exp_f32_e32 v71, v71
	v_pk_add_f32 v[76:77], v[76:77], v[180:181] op_sel_hi:[1,0]
	v_pk_add_f32 v[78:79], v[78:79], v[180:181] op_sel_hi:[1,0]
	v_pk_add_f32 v[68:69], v[68:69], v[180:181] op_sel_hi:[1,0]
	v_pk_add_f32 v[70:71], v[70:71], v[180:181] op_sel_hi:[1,0]
	v_add_co_u32_e32 v172, vcc, 0x16000, v172
	v_rcp_f32_e32 v76, v76
	v_rcp_f32_e32 v77, v77
	v_rcp_f32_e32 v78, v78
	v_rcp_f32_e32 v79, v79
	v_addc_co_u32_e32 v173, vcc, 0, v173, vcc
	v_rcp_f32_e32 v68, v68
	v_rcp_f32_e32 v69, v69
	v_rcp_f32_e32 v70, v70
	v_rcp_f32_e32 v71, v71
	v_pk_mul_f32 v[76:77], v[76:77], v[206:207] op_sel_hi:[1,0]
	v_pk_mul_f32 v[78:79], v[78:79], v[206:207] op_sel_hi:[1,0]
	v_pk_mul_f32 v[68:69], v[68:69], v[206:207] op_sel_hi:[1,0]
	v_pk_mul_f32 v[70:71], v[70:71], v[206:207] op_sel_hi:[1,0]
	v_pk_mul_f32 v[72:73], v[72:73], v[76:77]
	v_pk_mul_f32 v[74:75], v[74:75], v[78:79]
	v_pk_mul_f32 v[64:65], v[64:65], v[68:69]
	v_pk_mul_f32 v[66:67], v[66:67], v[70:71]
	v_cvt_pk_bf16_f32 v76, v72, v73
	v_cvt_pk_bf16_f32 v77, v74, v75
	v_cvt_pk_bf16_f32 v78, v64, v65
	v_cvt_pk_bf16_f32 v79, v66, v67
	flat_store_dwordx4 v[172:173], v[76:79]
	v_pk_mul_f32 v[56:57], v[60:61], v[56:57]
	v_pk_mul_f32 v[58:59], v[62:63], v[58:59]
	v_pk_mul_f32 v[48:49], v[52:53], v[48:49]
	v_pk_mul_f32 v[50:51], v[54:55], v[50:51]
	v_pk_mul_f32 v[60:61], v[60:61], v[192:193] op_sel_hi:[1,0]
	v_pk_mul_f32 v[62:63], v[62:63], v[192:193] op_sel_hi:[1,0]
	v_pk_mul_f32 v[52:53], v[52:53], v[192:193] op_sel_hi:[1,0]
	v_pk_mul_f32 v[54:55], v[54:55], v[192:193] op_sel_hi:[1,0]
	v_exp_f32_e32 v60, v60
	v_exp_f32_e32 v61, v61
	v_exp_f32_e32 v62, v62
	v_exp_f32_e32 v63, v63
	v_exp_f32_e32 v52, v52
	v_exp_f32_e32 v53, v53
	v_exp_f32_e32 v54, v54
	v_exp_f32_e32 v55, v55
	v_pk_add_f32 v[60:61], v[60:61], v[180:181] op_sel_hi:[1,0]
	v_pk_add_f32 v[62:63], v[62:63], v[180:181] op_sel_hi:[1,0]
	v_pk_add_f32 v[52:53], v[52:53], v[180:181] op_sel_hi:[1,0]
	v_pk_add_f32 v[54:55], v[54:55], v[180:181] op_sel_hi:[1,0]
	v_add_co_u32_e32 v172, vcc, 0x6e000, v172
	v_rcp_f32_e32 v60, v60
	v_rcp_f32_e32 v61, v61
	v_rcp_f32_e32 v62, v62
	v_rcp_f32_e32 v63, v63
	v_addc_co_u32_e32 v173, vcc, 0, v173, vcc
	v_rcp_f32_e32 v52, v52
	v_rcp_f32_e32 v53, v53
	v_rcp_f32_e32 v54, v54
	v_rcp_f32_e32 v55, v55
	v_pk_mul_f32 v[60:61], v[60:61], v[208:209] op_sel_hi:[1,0]
	v_pk_mul_f32 v[62:63], v[62:63], v[208:209] op_sel_hi:[1,0]
	v_pk_mul_f32 v[52:53], v[52:53], v[208:209] op_sel_hi:[1,0]
	v_pk_mul_f32 v[54:55], v[54:55], v[208:209] op_sel_hi:[1,0]
	v_pk_mul_f32 v[56:57], v[56:57], v[60:61]
	v_pk_mul_f32 v[58:59], v[58:59], v[62:63]
	v_pk_mul_f32 v[48:49], v[48:49], v[52:53]
	v_pk_mul_f32 v[50:51], v[50:51], v[54:55]
	v_cvt_pk_bf16_f32 v60, v56, v57
	v_cvt_pk_bf16_f32 v61, v58, v59
	v_cvt_pk_bf16_f32 v62, v48, v49
	v_cvt_pk_bf16_f32 v63, v50, v51
	flat_store_dwordx4 v[172:173], v[60:63]
	v_pk_mul_f32 v[40:41], v[44:45], v[40:41]
	v_pk_mul_f32 v[42:43], v[46:47], v[42:43]
	v_pk_mul_f32 v[32:33], v[36:37], v[32:33]
	v_pk_mul_f32 v[34:35], v[38:39], v[34:35]
	v_pk_mul_f32 v[44:45], v[44:45], v[194:195] op_sel_hi:[1,0]
	v_pk_mul_f32 v[46:47], v[46:47], v[194:195] op_sel_hi:[1,0]
	v_pk_mul_f32 v[36:37], v[36:37], v[194:195] op_sel_hi:[1,0]
	v_pk_mul_f32 v[38:39], v[38:39], v[194:195] op_sel_hi:[1,0]
	v_exp_f32_e32 v44, v44
	v_exp_f32_e32 v45, v45
	v_exp_f32_e32 v46, v46
	v_exp_f32_e32 v47, v47
	v_exp_f32_e32 v36, v36
	v_exp_f32_e32 v37, v37
; __device__ __forceinline__ u32x4 pack8(f32x4 v0, f32x4 v1) { u32x4 w; w.x = cvt_pk_bf16(v0[0], v0[1]); w.y = cvt_pk_bf16(v0[2], v0[3]); w.z = cvt_pk_bf16(v1[0], v1[1]); w.w = cvt_pk_bf16(v1[2], v1[3]); return w; }
;     __device__ __forceinline__ void operator()(Acc& acc, const Unit& u, int wr, int wc, int fr, int fq, PG8_LAS unsigned char* xl) const {
;     ...
;             for (int m = 0; m < 4; ++m) { const int rl = ai * HALF + wr * 64 + m * 16 + fr; const int row = u.r0 + rl; const float s = S[rl], cs = -LOG2E * s, s2 = s * s;
;                 f32x4 o[2];
; #pragma unroll
;                 for (int n = 0; n < 2; ++n) { const f32x4 g = acc[ai][0][m][n], gu = acc[ai][0][m][n] * acc[ai][1][m][n]; f32x4 r;
; #pragma unroll
;                     for (int e = 0; e < 4; ++e) r[e] = gu[e] * (s2 * __builtin_amdgcn_rcpf(1.f + __builtin_amdgcn_exp2f(cs * g[e])));
;                     o[n] = r; }
;                 *(u32x4*)(H + (size_t)row * ldc + (u.c0 >> 1) + wc * 32 + 8 * fq) = pack8(o[0], o[1]); }
	v_exp_f32_e32 v38, v38
	v_exp_f32_e32 v39, v39
	v_pk_add_f32 v[44:45], v[44:45], v[180:181] op_sel_hi:[1,0]
	v_pk_add_f32 v[46:47], v[46:47], v[180:181] op_sel_hi:[1,0]
	v_pk_add_f32 v[36:37], v[36:37], v[180:181] op_sel_hi:[1,0]
	v_pk_add_f32 v[38:39], v[38:39], v[180:181] op_sel_hi:[1,0]
	v_add_co_u32_e32 v172, vcc, 0x16000, v172
	v_rcp_f32_e32 v44, v44
	v_rcp_f32_e32 v45, v45
	v_rcp_f32_e32 v46, v46
	v_rcp_f32_e32 v47, v47
	v_addc_co_u32_e32 v173, vcc, 0, v173, vcc
	v_rcp_f32_e32 v36, v36
	v_rcp_f32_e32 v37, v37
	v_rcp_f32_e32 v38, v38
	v_rcp_f32_e32 v39, v39
	v_pk_mul_f32 v[44:45], v[44:45], v[210:211] op_sel_hi:[1,0]
	v_pk_mul_f32 v[46:47], v[46:47], v[210:211] op_sel_hi:[1,0]
	v_pk_mul_f32 v[36:37], v[36:37], v[210:211] op_sel_hi:[1,0]
	v_pk_mul_f32 v[38:39], v[38:39], v[210:211] op_sel_hi:[1,0]
	v_pk_mul_f32 v[40:41], v[40:41], v[44:45]
	v_pk_mul_f32 v[42:43], v[42:43], v[46:47]
	v_pk_mul_f32 v[32:33], v[32:33], v[36:37]
	v_pk_mul_f32 v[34:35], v[34:35], v[38:39]
	v_cvt_pk_bf16_f32 v44, v40, v41
	v_cvt_pk_bf16_f32 v45, v42, v43
	v_cvt_pk_bf16_f32 v46, v32, v33
	v_cvt_pk_bf16_f32 v47, v34, v35
	flat_store_dwordx4 v[172:173], v[44:47]
	v_pk_mul_f32 v[24:25], v[28:29], v[24:25]
	v_pk_mul_f32 v[26:27], v[30:31], v[26:27]
	v_pk_mul_f32 v[16:17], v[20:21], v[16:17]
	v_pk_mul_f32 v[18:19], v[22:23], v[18:19]
	v_pk_mul_f32 v[28:29], v[28:29], v[196:197] op_sel_hi:[1,0]
	v_pk_mul_f32 v[30:31], v[30:31], v[196:197] op_sel_hi:[1,0]
	v_pk_mul_f32 v[20:21], v[20:21], v[196:197] op_sel_hi:[1,0]
	v_pk_mul_f32 v[22:23], v[22:23], v[196:197] op_sel_hi:[1,0]
	v_exp_f32_e32 v28, v28
	v_exp_f32_e32 v29, v29
	v_exp_f32_e32 v30, v30
	v_exp_f32_e32 v31, v31
	v_exp_f32_e32 v20, v20
	v_exp_f32_e32 v21, v21
	v_exp_f32_e32 v22, v22
	v_exp_f32_e32 v23, v23
	v_pk_add_f32 v[28:29], v[28:29], v[180:181] op_sel_hi:[1,0]
	v_pk_add_f32 v[30:31], v[30:31], v[180:181] op_sel_hi:[1,0]
	v_pk_add_f32 v[20:21], v[20:21], v[180:181] op_sel_hi:[1,0]
	v_pk_add_f32 v[22:23], v[22:23], v[180:181] op_sel_hi:[1,0]
	v_add_co_u32_e32 v172, vcc, 0x16000, v172
	v_rcp_f32_e32 v28, v28
	v_rcp_f32_e32 v29, v29
	v_rcp_f32_e32 v30, v30
	v_rcp_f32_e32 v31, v31
	v_addc_co_u32_e32 v173, vcc, 0, v173, vcc
	v_rcp_f32_e32 v20, v20
	v_rcp_f32_e32 v21, v21
	v_rcp_f32_e32 v22, v22
	v_rcp_f32_e32 v23, v23
	v_pk_mul_f32 v[28:29], v[28:29], v[212:213] op_sel_hi:[1,0]
	v_pk_mul_f32 v[30:31], v[30:31], v[212:213] op_sel_hi:[1,0]
	v_pk_mul_f32 v[20:21], v[20:21], v[212:213] op_sel_hi:[1,0]
	v_pk_mul_f32 v[22:23], v[22:23], v[212:213] op_sel_hi:[1,0]
	v_pk_mul_f32 v[24:25], v[24:25], v[28:29]
	v_pk_mul_f32 v[26:27], v[26:27], v[30:31]
	v_pk_mul_f32 v[16:17], v[16:17], v[20:21]
	v_pk_mul_f32 v[18:19], v[18:19], v[22:23]
	v_cvt_pk_bf16_f32 v28, v24, v25
	v_cvt_pk_bf16_f32 v29, v26, v27
	v_cvt_pk_bf16_f32 v30, v16, v17
	v_cvt_pk_bf16_f32 v31, v18, v19
	flat_store_dwordx4 v[172:173], v[28:31]
	v_pk_mul_f32 v[8:9], v[12:13], v[8:9]
	v_pk_mul_f32 v[10:11], v[14:15], v[10:11]
	v_pk_mul_f32 v[0:1], v[4:5], v[0:1]
	v_pk_mul_f32 v[2:3], v[6:7], v[2:3]
	v_pk_mul_f32 v[12:13], v[12:13], v[198:199] op_sel_hi:[1,0]
	v_pk_mul_f32 v[14:15], v[14:15], v[198:199] op_sel_hi:[1,0]
	v_pk_mul_f32 v[4:5], v[4:5], v[198:199] op_sel_hi:[1,0]
	v_pk_mul_f32 v[6:7], v[6:7], v[198:199] op_sel_hi:[1,0]
	v_exp_f32_e32 v12, v12
	v_exp_f32_e32 v13, v13
	v_exp_f32_e32 v14, v14
	v_exp_f32_e32 v15, v15
	v_exp_f32_e32 v4, v4
	v_exp_f32_e32 v5, v5
	v_exp_f32_e32 v6, v6
	v_exp_f32_e32 v7, v7
	v_pk_add_f32 v[12:13], v[12:13], v[180:181] op_sel_hi:[1,0]
	v_pk_add_f32 v[14:15], v[14:15], v[180:181] op_sel_hi:[1,0]
	v_pk_add_f32 v[4:5], v[4:5], v[180:181] op_sel_hi:[1,0]
	v_pk_add_f32 v[6:7], v[6:7], v[180:181] op_sel_hi:[1,0]
	v_add_co_u32_e32 v172, vcc, 0x16000, v172
	v_rcp_f32_e32 v12, v12
	v_rcp_f32_e32 v13, v13
	v_rcp_f32_e32 v14, v14
	v_rcp_f32_e32 v15, v15
	v_addc_co_u32_e32 v173, vcc, 0, v173, vcc
	v_rcp_f32_e32 v4, v4
	v_rcp_f32_e32 v5, v5
	v_rcp_f32_e32 v6, v6
	v_rcp_f32_e32 v7, v7
	v_pk_mul_f32 v[12:13], v[12:13], v[214:215] op_sel_hi:[1,0]
	v_pk_mul_f32 v[14:15], v[14:15], v[214:215] op_sel_hi:[1,0]
	v_pk_mul_f32 v[4:5], v[4:5], v[214:215] op_sel_hi:[1,0]
	v_pk_mul_f32 v[6:7], v[6:7], v[214:215] op_sel_hi:[1,0]
	v_pk_mul_f32 v[8:9], v[8:9], v[12:13]
	v_pk_mul_f32 v[10:11], v[10:11], v[14:15]
	v_pk_mul_f32 v[0:1], v[0:1], v[4:5]
	v_pk_mul_f32 v[2:3], v[2:3], v[6:7]
	v_cvt_pk_bf16_f32 v12, v8, v9
	v_cvt_pk_bf16_f32 v13, v10, v11
	v_cvt_pk_bf16_f32 v14, v0, v1
	v_cvt_pk_bf16_f32 v15, v2, v3
	flat_store_dwordx4 v[172:173], v[12:15]
	s_andn2_b64 vcc, exec, s[6:7]
	s_mov_b64 s[2:3], -1
	s_cbranch_vccnz .LBB0_821
	s_andn2_b64 vcc, exec, s[10:11]
	s_cbranch_vccnz .LBB0_820
	s_barrier
	s_branch .LBB0_820
